# grid barrier 4 fast path: P4 waits only for the 4 same-pm P3 workgroups (same XCD verified at run time via XCC_ID mask, else original barrier)
# speedup vs baseline: 1.0226x; 1.0226x over previous
_Z9hymba_fwd4Args:
	s_load_dwordx2 s[52:53], s[0:1], 0x90
	s_load_dwordx4 s[28:31], s[0:1], 0x80
	s_add_u32 s6, s0, 0x98
	v_and_b32_e32 v254, 0x3ff, v0
	s_addc_u32 s7, s1, 0
	v_readfirstlane_b32 s56, v254
	v_cmp_gt_u32_e32 vcc, 32, v254
	s_and_saveexec_b64 s[4:5], vcc
	v_lshl_add_u32 v1, v254, 2, 0
	v_add_u32_e32 v1, 0x20000, v1
	v_mov_b32_e32 v2, 0
	ds_write_b32 v1, v2
	s_or_b64 exec, exec, s[4:5]
	s_load_dwordx2 s[10:11], s[0:1], 0x98
	s_load_dword s33, s[0:1], 0xa0
	s_waitcnt lgkmcnt(0)
	s_barrier
	s_add_u32 s54, s52, 0x1000
	s_getreg_b32 s3, hwreg(HW_REG_XCC_ID, 0, 4)
	s_addc_u32 s55, s53, 0
	s_and_b32 s3, s3, 15
	v_cmp_eq_u32_e64 s[92:93], 0, v254
	s_and_saveexec_b64 s[4:5], s[92:93]
	s_cbranch_execz .LBB0_5
	s_mov_b64 s[12:13], exec
	v_mbcnt_lo_u32_b32 v1, s12, 0
	v_mbcnt_hi_u32_b32 v1, s13, v1
	v_cmp_eq_u32_e32 vcc, 0, v1
	s_and_b64 s[14:15], exec, vcc
	s_mov_b64 exec, s[14:15]
	s_cbranch_execz .LBB0_5
	s_lshl_b32 s14, s3, 8
	s_bcnt1_i32_b64 s12, s[12:13]
	v_mov_b32_e32 v1, s14
	v_mov_b32_e32 v2, s12
	global_atomic_add v1, v2, s[54:55] offset:1024
	s_and_b32 s12, s2, 7
	s_lshl_b32 s12, s12, 3
	s_bfe_u32 s13, s2, 0x30003
	s_add_i32 s12, s12, s13
	s_lshl_b32 s12, s12, 6
	s_add_i32 s12, s12, 0x4000
	s_lshl_b32 s14, 1, s3
	v_mov_b32_e32 v1, s12
	v_mov_b32_e32 v2, s14
	global_atomic_or v1, v2, s[54:55]

.LBB0_243:
	s_or_b64 exec, exec, s[0:1]
	s_waitcnt lgkmcnt(0)
	v_mov_b32_e32 v0, v254
	s_barrier
	s_and_b32 s4, s2, 7
	s_lshl_b32 s4, s4, 3
	s_bfe_u32 s5, s2, 0x30003
	s_add_i32 s4, s4, s5
	s_lshl_b32 s4, s4, 6
	s_add_i32 s4, s4, 0x5000
	v_mov_b32_e32 v252, s4
	global_load_dword v253, v252, s[52:53] sc1
	s_mov_b32 s0, 0x46800000
	v_and_b32_e32 v1, 63, v0
	v_lshlrev_b32_e32 v1, 2, v1
	global_load_dword v2, v1, s[24:25]
	global_load_dword v3, v1, s[26:27]
	global_load_dword v4, v1, s[36:37]
	global_load_dword v5, v1, s[38:39]
	global_load_dword v6, v1, s[20:21]
	global_load_dword v7, v1, s[22:23]
	v_mbcnt_lo_u32_b32 v1, -1, 0
	v_mbcnt_hi_u32_b32 v1, -1, v1
	v_and_b32_e32 v8, 64, v1
	v_xor_b32_e32 v9, 1, v1
	v_add_u32_e32 v8, 64, v8
	v_xor_b32_e32 v10, 2, v1
	v_cmp_lt_i32_e32 vcc, v9, v8
	v_xor_b32_e32 v11, 4, v1
	v_xor_b32_e32 v12, 8, v1
	v_cndmask_b32_e32 v9, v1, v9, vcc
	v_cmp_lt_i32_e32 vcc, v10, v8
	v_xor_b32_e32 v13, 16, v1
	v_xor_b32_e32 v14, 32, v1
	v_cndmask_b32_e32 v10, v1, v10, vcc
	v_cmp_lt_i32_e32 vcc, v11, v8
	s_add_u32 s38, s52, 0x3800000
	s_addc_u32 s44, s53, 0
	v_cndmask_b32_e32 v11, v1, v11, vcc
	v_cmp_lt_i32_e32 vcc, v12, v8
	s_add_u32 s45, s52, 0x4800000
	s_addc_u32 s46, s53, 0
	v_cndmask_b32_e32 v12, v1, v12, vcc
	v_cmp_lt_i32_e32 vcc, v13, v8
	s_add_u32 s47, s52, 0x5800000
	s_addc_u32 s48, s53, 0
	v_cndmask_b32_e32 v13, v1, v13, vcc
	v_cmp_lt_i32_e32 vcc, v14, v8
	v_lshlrev_b32_e32 v8, 2, v9
	v_lshlrev_b32_e32 v9, 2, v10
	v_cndmask_b32_e32 v1, v1, v14, vcc
	v_lshlrev_b32_e32 v10, 2, v11
	v_lshlrev_b32_e32 v11, 2, v12
	v_lshlrev_b32_e32 v193, 2, v13
	v_lshlrev_b32_e32 v194, 2, v1
	s_add_u32 s49, s52, 0x6800000
	s_addc_u32 s50, s53, 0
	s_add_u32 s51, s52, 0x7800000
	s_addc_u32 s56, s53, 0
	s_add_u32 s57, s52, 0x8800000
	s_addc_u32 s58, s53, 0
	s_add_u32 s16, s52, 0xb800000
	s_mov_b32 s21, 0
	s_mov_b32 s39, 0x3fb8aa3b
	s_addc_u32 s17, s53, 0
	v_mov_b32_e32 v131, 0
	s_add_i32 s63, 0, 0x20040
	s_movk_i32 s64, 0x70
	v_mov_b32_e32 v195, 0x358637bd
	s_mov_b32 s65, 0x800000
	s_movk_i32 s66, 0xffef
	s_movk_i32 s67, 0xffe7
	v_mov_b32_e32 v196, 0x3f80
	v_mov_b32_e32 v197, 0x3f803f80
	v_mov_b32_e32 v198, 0x42800000
	v_mov_b32_e32 v199, 0xc6ea6000
	s_waitcnt vmcnt(4)
	v_mul_f32_e32 v1, v2, v3
	ds_bpermute_b32 v1, v8, v1
	s_waitcnt vmcnt(2)
	v_mul_f32_e32 v12, v4, v5
	s_waitcnt vmcnt(1)
	v_and_b32_e32 v13, 0x7fffffff, v6
	s_waitcnt vmcnt(0)
	v_and_b32_e32 v14, 0x7fffffff, v7
	ds_bpermute_b32 v12, v8, v12
	ds_bpermute_b32 v13, v8, v13
	ds_bpermute_b32 v8, v8, v14
	v_max_f32_e64 v6, |v6|, |v6|
	s_waitcnt lgkmcnt(3)
	v_fmac_f32_e32 v1, v2, v3
	s_waitcnt lgkmcnt(2)
	v_fmac_f32_e32 v12, v4, v5
	s_waitcnt lgkmcnt(1)
	v_max_f32_e32 v2, v13, v13
	v_max_f32_e64 v7, |v7|, |v7|
	s_waitcnt lgkmcnt(0)
	v_max_f32_e32 v3, v8, v8
	ds_bpermute_b32 v4, v9, v1
	ds_bpermute_b32 v5, v9, v12
	v_max_f32_e32 v2, v6, v2
	v_max_f32_e32 v3, v7, v3
	ds_bpermute_b32 v6, v9, v2
	ds_bpermute_b32 v7, v9, v3
	s_waitcnt lgkmcnt(3)
	v_add_f32_e32 v1, v1, v4
	s_waitcnt lgkmcnt(2)
	v_add_f32_e32 v4, v12, v5
	ds_bpermute_b32 v5, v10, v1
	ds_bpermute_b32 v8, v10, v4
	s_waitcnt lgkmcnt(3)
	v_max_f32_e32 v6, v6, v6
	s_waitcnt lgkmcnt(2)
	v_max_f32_e32 v7, v7, v7
	v_max_f32_e32 v2, v2, v6
	v_max_f32_e32 v3, v3, v7
	ds_bpermute_b32 v6, v10, v2
	ds_bpermute_b32 v7, v10, v3
	s_waitcnt lgkmcnt(3)
	v_add_f32_e32 v1, v1, v5
	s_waitcnt lgkmcnt(2)
	v_add_f32_e32 v4, v4, v8
	ds_bpermute_b32 v5, v11, v1
	ds_bpermute_b32 v8, v11, v4
	s_waitcnt lgkmcnt(3)
	v_max_f32_e32 v6, v6, v6
	s_waitcnt lgkmcnt(2)
	v_max_f32_e32 v7, v7, v7
	v_max_f32_e32 v2, v2, v6
	v_max_f32_e32 v3, v3, v7
	ds_bpermute_b32 v6, v11, v2
	ds_bpermute_b32 v7, v11, v3
	s_waitcnt lgkmcnt(3)
	v_add_f32_e32 v1, v1, v5
	s_waitcnt lgkmcnt(2)
	v_add_f32_e32 v4, v4, v8
	ds_bpermute_b32 v5, v193, v1
	ds_bpermute_b32 v8, v193, v4
	s_waitcnt lgkmcnt(3)
	v_max_f32_e32 v6, v6, v6
	s_waitcnt lgkmcnt(2)
	v_max_f32_e32 v7, v7, v7
	v_max_f32_e32 v2, v2, v6
	v_max_f32_e32 v3, v3, v7
	ds_bpermute_b32 v6, v193, v2
	ds_bpermute_b32 v7, v193, v3
	s_waitcnt lgkmcnt(3)
	v_add_f32_e32 v1, v1, v5
	s_waitcnt lgkmcnt(2)
	v_add_f32_e32 v4, v4, v8
	ds_bpermute_b32 v5, v194, v1
	ds_bpermute_b32 v8, v194, v4
	s_waitcnt lgkmcnt(3)
	v_max_f32_e32 v6, v6, v6
	s_waitcnt lgkmcnt(2)
	v_max_f32_e32 v7, v7, v7
	v_max_f32_e32 v2, v2, v6
	v_max_f32_e32 v3, v3, v7
	s_waitcnt lgkmcnt(1)
	v_add_f32_e32 v1, v1, v5
	s_waitcnt lgkmcnt(0)
	v_add_f32_e32 v4, v4, v8
	ds_bpermute_b32 v5, v194, v2
	ds_bpermute_b32 v6, v194, v3
	v_mul_f32_e32 v1, 0x3fb8aa3b, v1
	v_mul_f32_e32 v4, 0x3fb8aa3b, v4
	v_exp_f32_e32 v1, v1
	v_exp_f32_e32 v4, v4
	s_waitcnt lgkmcnt(1)
	v_max_f32_e32 v5, v5, v5
	s_waitcnt lgkmcnt(0)
	v_max_f32_e32 v6, v6, v6
	v_max_f32_e32 v2, v2, v5
	v_sub_f32_e32 v1, v1, v4
	v_max_f32_e32 v3, v3, v6
	v_add_f32_e32 v180, 0x3e4ccccd, v1
	v_mul_f32_e32 v1, 0x41000000, v2
	v_mul_f32_e32 v1, v1, v3
	v_mul_f32_e32 v1, 0x3f828f5c, v1
	v_mov_b32_e32 v2, 0x41c80000
	v_fmac_f32_e32 v2, 2.0, v1
	v_mul_f32_e32 v1, 4.0, v2
	v_ceil_f32_e32 v1, v1
	v_mov_b32_e32 v3, 0x46800000
	v_cmp_nle_f32_e32 vcc, s0, v1
	v_mov_b32_e32 v181, v180
	s_nop 0
	v_cndmask_b32_e32 v1, v3, v1, vcc
	s_nop 0
	v_readfirstlane_b32 s59, v1
	v_mul_f32_e32 v1, 0x41800000, v2
	v_ceil_f32_e32 v1, v1
	v_cmp_nle_f32_e32 vcc, s0, v1
	s_nop 1
	v_cndmask_b32_e32 v1, v3, v1, vcc
	s_nop 0
	v_readfirstlane_b32 s60, v1
	v_mul_f32_e32 v1, 0x42800000, v2
	v_ceil_f32_e32 v1, v1
	v_cmp_nle_f32_e32 vcc, s0, v1
	s_nop 1
	v_cndmask_b32_e32 v1, v3, v1, vcc
	s_nop 0
	v_readfirstlane_b32 s61, v1
	v_mul_f32_e32 v1, 0x43800000, v2
	v_ceil_f32_e32 v1, v1
	v_cmp_nle_f32_e32 vcc, s0, v1
	v_cmp_eq_u32_e64 s[0:1], 0, v0
	s_nop 0
	v_cndmask_b32_e32 v1, v3, v1, vcc
	s_nop 0
	v_readfirstlane_b32 s62, v1
	s_branch .LBB0_246

.LBB0_311:
	s_waitcnt vmcnt(0)
	s_waitcnt lgkmcnt(0)
	s_barrier
	s_cmpk_gt_u32 s2, 0xff
	s_cbranch_scc1 .Lxa_skip
	v_readfirstlane_b32 s4, v254
	s_and_b32 s5, s2, 7
	s_lshr_b32 s4, s4, 6
	s_lshl_b32 s5, s5, 3
	s_bfe_u32 s6, s2, 0x30003
	s_add_i32 s5, s5, s6
	s_lshr_b32 s6, s2, 6
	s_lshl_b32 s5, s5, 8
	s_lshr_b32 s7, s4, 2
	s_lshl_b32 s7, s7, 6
	s_add_i32 s5, s5, s7
	s_lshl_b32 s6, s6, 8
	s_and_b32 s7, s4, 3
	s_lshl_b32 s7, s7, 6
	s_add_i32 s6, s6, s7
	v_and_b32_e32 v200, 15, v254
	v_bfe_u32 v201, v254, 4, 2
	v_or_b32_e32 v200, s5, v200
	v_lshl_or_b32 v201, v201, 3, s6
	v_lshlrev_b32_e32 v200, 10, v200
	v_add_u32_e32 v200, v200, v201
	v_lshlrev_b32_e32 v200, 2, v200
	v_add_u32_e32 v201, 0x10000, v200
	v_add_u32_e32 v202, 0x20000, v200
	v_add_u32_e32 v203, 0x30000, v200
	v_add_u32_e32 v204, 0x80000, v200
	v_add_u32_e32 v205, 0x90000, v200
	v_add_u32_e32 v206, 0xa0000, v200
	v_add_u32_e32 v207, 0xb0000, v200
	s_cmp_eq_u32 s4, 0
	s_cbranch_scc1 .Lxa_w0
	global_load_dwordx4 v[124:127], v200, s[12:13] nt
	global_load_dwordx4 v[120:123], v200, s[12:13] offset:16 nt
	global_load_dwordx4 v[116:119], v200, s[12:13] offset:128 nt
	global_load_dwordx4 v[112:115], v200, s[12:13] offset:144 nt
	global_load_dwordx4 v[108:111], v201, s[12:13] nt
	global_load_dwordx4 v[104:107], v201, s[12:13] offset:16 nt
	global_load_dwordx4 v[100:103], v201, s[12:13] offset:128 nt
	global_load_dwordx4 v[96:99], v201, s[12:13] offset:144 nt
	global_load_dwordx4 v[92:95], v202, s[12:13] nt
	global_load_dwordx4 v[88:91], v202, s[12:13] offset:16 nt
	global_load_dwordx4 v[84:87], v202, s[12:13] offset:128 nt
	global_load_dwordx4 v[80:83], v202, s[12:13] offset:144 nt
	global_load_dwordx4 v[76:79], v203, s[12:13] nt
	global_load_dwordx4 v[72:75], v203, s[12:13] offset:16 nt
	global_load_dwordx4 v[68:71], v203, s[12:13] offset:128 nt
	global_load_dwordx4 v[64:67], v203, s[12:13] offset:144 nt
	global_load_dwordx4 v[60:63], v204, s[12:13] nt
	global_load_dwordx4 v[56:59], v204, s[12:13] offset:16 nt
	global_load_dwordx4 v[52:55], v204, s[12:13] offset:128 nt
	global_load_dwordx4 v[48:51], v204, s[12:13] offset:144 nt
	global_load_dwordx4 v[44:47], v205, s[12:13] nt
	global_load_dwordx4 v[40:43], v205, s[12:13] offset:16 nt
	global_load_dwordx4 v[36:39], v205, s[12:13] offset:128 nt
	global_load_dwordx4 v[32:35], v205, s[12:13] offset:144 nt
	global_load_dwordx4 v[28:31], v206, s[12:13] nt
	global_load_dwordx4 v[24:27], v206, s[12:13] offset:16 nt
	global_load_dwordx4 v[20:23], v206, s[12:13] offset:128 nt
	s_branch .Lxa_skip
.Lxa_w0:
	v_readfirstlane_b32 s5, v253
	s_bcnt1_i32_b32 s5, s5
	s_cmp_eq_u32 s5, 1
	s_cbranch_scc1 .Lxa_skip
	s_mov_b64 s[8:9], exec
	s_mov_b64 exec, 1
	v_mov_b32_e32 v208, 0x7000
	v_mov_b32_e32 v209, 1
	global_atomic_add v208, v209, s[52:53]
	s_mov_b64 exec, s[8:9]

.LBB0_363:
	s_or_b64 exec, exec, s[0:1]
	s_waitcnt vmcnt(1)
	v_mov_b32_e32 v144, v254
	s_waitcnt lgkmcnt(0)
	v_cndmask_b32_e64 v240, 0, 1, s[94:95]
	s_barrier
	v_mov_b32_e32 v255, 0x7000
	global_load_dword v255, v255, s[52:53] sc1
	s_cmpk_gt_u32 s2, 0xff
	s_cbranch_scc1 .Lxb_done
	v_readfirstlane_b32 s4, v254
	s_nop 0
	s_lshr_b32 s4, s4, 6
	s_cmp_lg_u32 s4, 0
	s_cbranch_scc1 .Lxb_low
	global_load_dwordx4 v[124:127], v200, s[12:13] nt
	global_load_dwordx4 v[120:123], v200, s[12:13] offset:16 nt
	global_load_dwordx4 v[116:119], v200, s[12:13] offset:128 nt
	global_load_dwordx4 v[112:115], v200, s[12:13] offset:144 nt
	global_load_dwordx4 v[108:111], v201, s[12:13] nt
	global_load_dwordx4 v[104:107], v201, s[12:13] offset:16 nt
	global_load_dwordx4 v[100:103], v201, s[12:13] offset:128 nt
	global_load_dwordx4 v[96:99], v201, s[12:13] offset:144 nt
	global_load_dwordx4 v[92:95], v202, s[12:13] nt
	global_load_dwordx4 v[88:91], v202, s[12:13] offset:16 nt
	global_load_dwordx4 v[84:87], v202, s[12:13] offset:128 nt
	global_load_dwordx4 v[80:83], v202, s[12:13] offset:144 nt
	global_load_dwordx4 v[76:79], v203, s[12:13] nt
	global_load_dwordx4 v[72:75], v203, s[12:13] offset:16 nt
	global_load_dwordx4 v[68:71], v203, s[12:13] offset:128 nt
	global_load_dwordx4 v[64:67], v203, s[12:13] offset:144 nt
	global_load_dwordx4 v[60:63], v204, s[12:13] nt
	global_load_dwordx4 v[56:59], v204, s[12:13] offset:16 nt
	global_load_dwordx4 v[52:55], v204, s[12:13] offset:128 nt
	global_load_dwordx4 v[48:51], v204, s[12:13] offset:144 nt
	global_load_dwordx4 v[44:47], v205, s[12:13] nt
	global_load_dwordx4 v[40:43], v205, s[12:13] offset:16 nt
	global_load_dwordx4 v[36:39], v205, s[12:13] offset:128 nt
	global_load_dwordx4 v[32:35], v205, s[12:13] offset:144 nt
	global_load_dwordx4 v[28:31], v206, s[12:13] nt
	global_load_dwordx4 v[24:27], v206, s[12:13] offset:16 nt
	global_load_dwordx4 v[20:23], v206, s[12:13] offset:128 nt

.LBB0_405:
	s_waitcnt vmcnt(0)
	s_waitcnt lgkmcnt(0)
	s_barrier
	s_and_saveexec_b64 s[4:5], s[92:93]
	s_cbranch_execz .LBB0_457
	s_cmpk_gt_u32 s2, 0xff
	s_cbranch_scc1 .Lgb_slow
	v_readfirstlane_b32 s9, v255
	s_cmp_lg_u32 s9, 0
	s_cbranch_scc1 .Lgb_slow
	s_and_b32 s8, s2, 7
	s_lshl_b32 s8, s8, 3
	s_bfe_u32 s9, s2, 0x30003
	s_add_i32 s8, s8, s9
	s_lshl_b32 s8, s8, 6
	s_add_i32 s8, s8, 0x6000
	v_mov_b32_e32 v0, s8
	v_mov_b32_e32 v1, 1
	global_atomic_add v0, v1, s[52:53]
	s_mov_b32 s9, 0
.Lgb_spin:
	global_load_dword v2, v0, s[52:53] sc1
	s_waitcnt vmcnt(0)
	v_readfirstlane_b32 s8, v2
	s_cmp_ge_u32 s8, 4
	s_cbranch_scc1 .Lgb_done
	s_sleep 1
	s_add_i32 s9, s9, 1
	s_cmp_lt_u32 s9, 0x40000
	s_cbranch_scc1 .Lgb_spin
.Lgb_done:
	buffer_inv sc1
	s_waitcnt vmcnt(0)
	s_branch .LBB0_457
.Lgb_slow:
	s_add_i32 s8, 0, 0x20020
	v_mov_b32_e32 v0, s8
	s_waitcnt vmcnt(0) expcnt(0) lgkmcnt(0)
	ds_read_b32 v2, v0
	s_add_i32 s8, 0, 0x20024
	v_mov_b32_e32 v0, s8
	ds_read_b32 v0, v0
	s_waitcnt lgkmcnt(1)
	v_cmp_ne_u32_e32 vcc, 0, v2
	s_cbranch_vccnz .LBB0_421
	s_add_u32 s8, s52, 0x1200
	s_addc_u32 s9, s53, 0
	s_add_u32 s12, s52, 0x1400
	s_addc_u32 s13, s53, 0
	s_add_u32 s18, s52, 0x1500
	s_addc_u32 s19, s53, 0
	s_add_u32 s20, s52, 0x1600
	s_addc_u32 s21, s53, 0
	s_add_u32 s22, s52, 0x1700
	s_addc_u32 s23, s53, 0
	s_add_u32 s24, s52, 0x1800
	s_addc_u32 s25, s53, 0
	s_add_u32 s26, s52, 0x1900
	s_addc_u32 s27, s53, 0
	s_add_u32 s28, s52, 0x1a00
	s_addc_u32 s29, s53, 0
	s_add_u32 s36, s52, 0x1b00
	s_addc_u32 s37, s53, 0
	s_add_u32 s38, s52, 0x1c00
	s_addc_u32 s39, s53, 0
	s_add_u32 s40, s52, 0x1d00
	s_addc_u32 s41, s53, 0
	s_add_u32 s42, s52, 0x1e00
	s_addc_u32 s43, s53, 0
	s_add_u32 s44, s52, 0x1f00
	s_addc_u32 s45, s53, 0
	s_add_u32 s46, s52, 0x2000
	s_addc_u32 s47, s53, 0
	s_add_u32 s48, s52, 0x2100
	s_addc_u32 s49, s53, 0
	s_add_u32 s50, s52, 0x2200
	s_addc_u32 s51, s53, 0
	s_mul_i32 s11, s11, s33
	s_add_u32 s56, s52, 0x2300
	s_mul_i32 s11, s11, s10
	s_addc_u32 s57, s53, 0
	s_mov_b32 s33, 1
	v_mov_b32_e32 v16, 0
	s_branch .LBB0_409
